# D1 GEMM fused-norm epilogue: norm gains loaded once instead of 32 dependent load+wait round trips per tile
# speedup vs baseline: 1.0079x; 1.0038x over previous
.LBB0_1409:
	s_or_b64 exec, exec, s[6:7]
	v_lshlrev_b32_e32 v155, 2, v148
	s_waitcnt lgkmcnt(0)
	v_or_b32_e32 v18, s48, v155
	v_lshlrev_b32_e32 v16, 2, v18
	s_waitcnt vmcnt(0)
	s_barrier
	v_min_u32_e32 v248, 0xb0, v16
	global_load_dwordx4 v[224:227], v16, s[12:13]
	global_load_dwordx4 v[228:231], v16, s[12:13] offset:64
	global_load_dwordx4 v[232:235], v248, s[30:31]
	global_load_dwordx4 v[236:239], v248, s[34:35]
	global_load_dwordx4 v[240:243], v248, s[30:31] offset:64
	global_load_dwordx4 v[244:247], v248, s[34:35] offset:64
	s_add_u32 s40, s36, 0x15000000
	ds_read_b128 v[20:23], v149
	ds_read_b128 v[138:141], v149 offset:16
	ds_read2_b64 v[142:145], v149 offset0:4 offset1:6
	s_addc_u32 s41, s37, 0
	s_add_u32 s36, s14, 0x15800000
	s_addc_u32 s37, s15, 0
	s_add_u32 s38, s10, 0x15c00000
	s_addc_u32 s39, s11, 0
	s_ashr_i32 s27, s26, 31
	s_waitcnt lgkmcnt(2)
	v_mov_b32_e32 v146, v20
	s_waitcnt lgkmcnt(0)
	v_mov_b32_e32 v147, v142
	v_mov_b32_e32 v142, v138
	v_mov_b32_e32 v143, v144
	v_mov_b32_e32 v129, 0
	v_pk_add_f32 v[20:21], v[20:21], v[138:139]
	v_add_f32_e32 v22, v22, v140
	s_lshl_b64 s[42:43], s[26:27], 8
	v_pk_add_f32 v[138:139], v[146:147], v[142:143]
	v_mov_b32_e32 v141, 0x358637bd
	s_mov_b32 s6, 0x3c800000
	v_mov_b32_e32 v17, v129
	v_mov_b32_e32 v19, v129
	v_pk_mov_b32 v[22:23], v[20:21], v[22:23] op_sel:[1,0]
	v_lshl_add_u64 v[20:21], s[42:43], 0, v[128:129]
	v_add_f32_e32 v129, v138, v139
	s_mov_b32 s49, 0x800000
	v_pk_mul_f32 v[22:23], v[22:23], s[6:7] op_sel_hi:[1,0]
	v_fmac_f32_e32 v141, 0x3c000000, v129
	v_fma_f32 v23, -v22, v22, v23
	v_mul_f32_e32 v129, 0x4b800000, v141
	v_cmp_gt_f32_e32 vcc, s49, v141
	s_cmp_lt_u32 s3, 2
	v_lshlrev_b64 v[138:139], 8, v[20:21]
	v_max_f32_e32 v23, 0, v23
	v_cndmask_b32_e32 v129, v141, v129, vcc
	v_lshlrev_b32_e32 v18, 1, v18
	s_cselect_b64 s[44:45], -1, 0
	s_cmp_gt_u32 s3, 1
	v_lshl_add_u64 v[138:139], s[40:41], 0, v[138:139]
	v_add_f32_e32 v23, 0x358637bd, v23
	v_rsq_f32_e32 v129, v129
	s_cselect_b64 s[14:15], -1, 0
	s_cmp_eq_u32 s3, 2
	v_lshl_add_u64 v[140:141], v[138:139], 0, v[18:19]
	v_mul_f32_e32 v138, 0x4b800000, v23
	v_cmp_gt_f32_e64 s[10:11], s49, v23
	s_cselect_b64 s[6:7], -1, 0
	v_cndmask_b32_e64 v19, 0, 1, s[6:7]
	v_cndmask_b32_e64 v23, v23, v138, s[10:11]
	v_rsq_f32_e32 v23, v23
	v_cmp_ne_u32_e64 s[6:7], 1, v19
	v_mul_f32_e32 v19, 0x45800000, v129
	v_cndmask_b32_e32 v144, v129, v19, vcc
	v_pk_mul_f32 v[146:147], v[136:137], v[144:145] op_sel_hi:[1,0]
	v_pk_mul_f32 v[160:161], v[134:135], v[144:145] op_sel_hi:[1,0]
	s_and_b64 s[8:9], exec, s[14:15]
	v_mul_f32_e32 v19, 0x45800000, v23
	s_mov_b64 s[46:47], -1
	v_lshlrev_b64 v[142:143], 7, v[20:21]
	v_cndmask_b32_e64 v138, v23, v19, s[10:11]
	s_mov_b64 vcc, s[8:9]
	s_waitcnt vmcnt(0)
	v_mov_b64_e32 v[156:157], v[224:225]
	v_mov_b64_e32 v[158:159], v[226:227]
	v_pk_mul_f32 v[158:159], v[158:159], v[160:161]
	v_pk_mul_f32 v[146:147], v[156:157], v[146:147]
	s_nop 0
	v_cvt_pk_bf16_f32 v146, v146, v147
	v_cvt_pk_bf16_f32 v147, v158, v159
	global_store_dwordx2 v[140:141], v[146:147], off
	s_cbranch_vccz .LBB0_1413
	s_and_b64 vcc, exec, s[6:7]
	s_cbranch_vccnz .LBB0_1412
	v_lshlrev_b64 v[20:21], 6, v[20:21]
	v_lshl_add_u64 v[20:21], s[38:39], 0, v[20:21]
	v_lshlrev_b32_e32 v146, 2, v155
	v_mov_b32_e32 v147, 0
	s_mov_b32 s8, 0x3d000000
	v_lshl_add_u64 v[20:21], v[20:21], 0, v[146:147]
	v_pk_mul_f32 v[158:159], v[124:125], s[8:9] op_sel_hi:[1,0]
	v_pk_mul_f32 v[156:157], v[126:127], s[8:9] op_sel_hi:[1,0]
	global_store_dwordx4 v[20:21], v[156:159], off sc1

.LBB0_1413:
	v_mov_b32_e32 v145, v144
	v_mov_b32_e32 v139, v138
	v_lshl_add_u64 v[20:21], s[12:13], 0, v[16:17]
	s_andn2_b64 vcc, exec, s[46:47]
	v_lshl_add_u64 v[142:143], s[36:37], 0, v[142:143]
	s_cbranch_vccnz .LBB0_1415
	v_mov_b64_e32 v[156:157], v[232:233]
	v_mov_b64_e32 v[158:159], v[234:235]
	v_mov_b64_e32 v[160:161], v[236:237]
	v_mov_b64_e32 v[162:163], v[238:239]
	v_sub_f32_e32 v147, v125, v22
	v_sub_f32_e32 v146, v124, v22
	v_sub_f32_e32 v165, v127, v22
	v_sub_f32_e32 v164, v126, v22
	v_mov_b32_e32 v166, v138
	v_mov_b32_e32 v167, v138
	v_pk_mul_f32 v[164:165], v[164:165], v[138:139]
	v_pk_mul_f32 v[146:147], v[146:147], v[166:167]
	v_mov_b32_e32 v19, 0
	v_pk_fma_f32 v[146:147], v[146:147], v[158:159], v[162:163]
	v_pk_fma_f32 v[156:157], v[164:165], v[156:157], v[160:161]
	s_nop 0
	v_cvt_pk_bf16_f32 v156, v156, v157
	v_cvt_pk_bf16_f32 v157, v146, v147
	v_lshl_add_u64 v[146:147], v[142:143], 0, v[18:19]
	global_store_dwordx2 v[146:147], v[156:157], off
.LBB0_1415:
	v_mov_b64_e32 v[156:157], v[228:229]
	v_mov_b64_e32 v[158:159], v[230:231]
	v_mov_b32_e32 v146, v144
	v_mov_b32_e32 v147, v144
	v_pk_mul_f32 v[144:145], v[132:133], v[144:145]
	v_pk_mul_f32 v[146:147], v[130:131], v[146:147]
	v_cndmask_b32_e64 v17, 0, 1, s[44:45]
	v_cmp_ne_u32_e64 s[8:9], 1, v17
	s_andn2_b64 vcc, exec, s[44:45]
	v_pk_mul_f32 v[146:147], v[146:147], v[158:159]
	v_pk_mul_f32 v[144:145], v[144:145], v[156:157]
	s_nop 0
	v_cvt_pk_bf16_f32 v144, v144, v145
	v_cvt_pk_bf16_f32 v145, v146, v147
	global_store_dwordx2 v[140:141], v[144:145], off offset:32
	s_cbranch_vccnz .LBB0_1417
	v_mov_b64_e32 v[144:145], v[240:241]
	v_mov_b64_e32 v[146:147], v[242:243]
	v_mov_b64_e32 v[156:157], v[244:245]
	v_mov_b64_e32 v[158:159], v[246:247]
	v_sub_f32_e32 v141, v121, v22
	v_sub_f32_e32 v140, v120, v22
	v_sub_f32_e32 v23, v123, v22
	v_sub_f32_e32 v22, v122, v22
	v_pk_mul_f32 v[22:23], v[22:23], v[138:139]
	v_mov_b32_e32 v139, v138
	v_pk_mul_f32 v[138:139], v[140:141], v[138:139]
	v_mov_b32_e32 v19, 0
	v_pk_fma_f32 v[138:139], v[138:139], v[146:147], v[158:159]
	v_pk_fma_f32 v[22:23], v[22:23], v[144:145], v[156:157]
	s_nop 0
	v_cvt_pk_bf16_f32 v22, v22, v23
	v_cvt_pk_bf16_f32 v23, v138, v139
	v_lshl_add_u64 v[138:139], v[142:143], 0, v[18:19]
	global_store_dwordx2 v[138:139], v[22:23], off offset:32
.LBB0_1417:
	v_mov_b64_e32 v[156:157], v[224:225]
	v_mov_b64_e32 v[158:159], v[226:227]
	v_or_b32_e32 v22, 16, v128
	v_mov_b32_e32 v23, 0
	v_lshl_add_u64 v[146:147], s[42:43], 0, v[22:23]
	v_lshl_add_u32 v22, v22, 6, 0
	ds_read_b128 v[138:141], v22
	ds_read_b128 v[160:163], v22 offset:16
	ds_read2_b64 v[164:167], v22 offset0:4 offset1:6
	v_cndmask_b32_e64 v129, 0, 1, s[14:15]
	v_mov_b32_e32 v17, 0x358637bd
	s_waitcnt lgkmcnt(2)
	v_mov_b32_e32 v142, v138
	s_waitcnt lgkmcnt(1)
	v_pk_add_f32 v[138:139], v[138:139], v[160:161]
	s_waitcnt lgkmcnt(0)
	v_mov_b32_e32 v143, v164
	v_mov_b32_e32 v164, v160
	v_mov_b32_e32 v165, v166
	v_add_f32_e32 v140, v140, v162
	v_pk_add_f32 v[142:143], v[142:143], v[164:165]
	s_mov_b32 s12, 0x3c800000
	v_cmp_ne_u32_e64 s[10:11], 1, v129
	v_pk_mov_b32 v[138:139], v[138:139], v[140:141] op_sel:[1,0]
	v_add_f32_e32 v129, v142, v143
	s_mov_b32 s27, 0x800000
	v_pk_mul_f32 v[138:139], v[138:139], s[12:13] op_sel_hi:[1,0]
	v_fmac_f32_e32 v17, 0x3c000000, v129
	v_fma_f32 v129, -v138, v138, v139
	v_mul_f32_e32 v139, 0x4b800000, v17
	v_cmp_gt_f32_e64 s[12:13], s27, v17
	v_max_f32_e32 v129, 0, v129
	v_add_f32_e32 v129, 0x358637bd, v129
	v_cndmask_b32_e64 v17, v17, v139, s[12:13]
	v_rsq_f32_e32 v17, v17
	s_andn2_b64 vcc, exec, s[14:15]
	v_mul_f32_e32 v139, 0x4b800000, v129
	v_cmp_gt_f32_e64 s[14:15], s27, v129
	v_mov_b32_e32 v19, v23
	v_lshlrev_b64 v[22:23], 8, v[146:147]
	v_cndmask_b32_e64 v129, v129, v139, s[14:15]
	v_lshl_add_u64 v[22:23], s[40:41], 0, v[22:23]
	v_rsq_f32_e32 v129, v129
	v_lshl_add_u64 v[140:141], v[22:23], 0, v[18:19]
	v_mul_f32_e32 v19, 0x45800000, v17
	v_cndmask_b32_e64 v142, v17, v19, s[12:13]
	v_pk_mul_f32 v[160:161], v[116:117], v[142:143] op_sel_hi:[1,0]
	v_pk_mul_f32 v[162:163], v[118:119], v[142:143] op_sel_hi:[1,0]
	v_mul_f32_e32 v17, 0x45800000, v129
	v_lshlrev_b64 v[144:145], 7, v[146:147]
	v_cndmask_b32_e64 v22, v129, v17, s[14:15]
	s_mov_b64 s[12:13], -1
	v_pk_mul_f32 v[158:159], v[158:159], v[162:163]
	v_pk_mul_f32 v[156:157], v[156:157], v[160:161]
	s_nop 0
	v_cvt_pk_bf16_f32 v156, v156, v157
	v_cvt_pk_bf16_f32 v157, v158, v159
	global_store_dwordx2 v[140:141], v[156:157], off
	s_cbranch_vccnz .LBB0_1421
	s_and_b64 vcc, exec, s[6:7]
	s_cbranch_vccnz .LBB0_1420
	v_lshlrev_b64 v[146:147], 6, v[146:147]
	v_lshl_add_u64 v[146:147], s[38:39], 0, v[146:147]
	v_lshlrev_b32_e32 v156, 2, v155
	v_mov_b32_e32 v157, 0
	s_mov_b32 s12, 0x3d000000
	v_lshl_add_u64 v[146:147], v[146:147], 0, v[156:157]
	v_pk_mul_f32 v[158:159], v[108:109], s[12:13] op_sel_hi:[1,0]
	v_pk_mul_f32 v[156:157], v[110:111], s[12:13] op_sel_hi:[1,0]
	global_store_dwordx4 v[146:147], v[156:159], off sc1

.LBB0_1421:
	v_mov_b32_e32 v143, v142
	v_mov_b32_e32 v23, v22
	s_andn2_b64 vcc, exec, s[12:13]
	v_lshl_add_u64 v[144:145], s[36:37], 0, v[144:145]
	s_cbranch_vccnz .LBB0_1423
	v_mov_b64_e32 v[156:157], v[232:233]
	v_mov_b64_e32 v[158:159], v[234:235]
	v_mov_b64_e32 v[160:161], v[236:237]
	v_mov_b64_e32 v[162:163], v[238:239]
	v_sub_f32_e32 v147, v109, v138
	v_sub_f32_e32 v146, v108, v138
	v_sub_f32_e32 v165, v111, v138
	v_sub_f32_e32 v164, v110, v138
	v_mov_b32_e32 v166, v22
	v_mov_b32_e32 v167, v22
	v_pk_mul_f32 v[164:165], v[164:165], v[22:23]
	v_pk_mul_f32 v[146:147], v[146:147], v[166:167]
	v_mov_b32_e32 v19, 0
	v_pk_fma_f32 v[146:147], v[146:147], v[158:159], v[162:163]
	v_pk_fma_f32 v[156:157], v[164:165], v[156:157], v[160:161]
	s_nop 0
	v_cvt_pk_bf16_f32 v156, v156, v157
	v_cvt_pk_bf16_f32 v157, v146, v147
	v_lshl_add_u64 v[146:147], v[144:145], 0, v[18:19]
	global_store_dwordx2 v[146:147], v[156:157], off
.LBB0_1423:
	v_mov_b64_e32 v[156:157], v[228:229]
	v_mov_b64_e32 v[158:159], v[230:231]
	v_mov_b32_e32 v146, v142
	v_mov_b32_e32 v147, v142
	v_pk_mul_f32 v[142:143], v[112:113], v[142:143]
	v_pk_mul_f32 v[146:147], v[114:115], v[146:147]
	s_and_b64 vcc, exec, s[8:9]
	v_pk_mul_f32 v[146:147], v[146:147], v[158:159]
	v_pk_mul_f32 v[142:143], v[142:143], v[156:157]
	s_nop 0
	v_cvt_pk_bf16_f32 v142, v142, v143
	v_cvt_pk_bf16_f32 v143, v146, v147
	global_store_dwordx2 v[140:141], v[142:143], off offset:32
	s_cbranch_vccnz .LBB0_1425
	v_mov_b64_e32 v[140:141], v[240:241]
	v_mov_b64_e32 v[142:143], v[242:243]
	v_mov_b64_e32 v[156:157], v[244:245]
	v_mov_b64_e32 v[158:159], v[246:247]
	v_sub_f32_e32 v147, v105, v138
	v_sub_f32_e32 v146, v104, v138
	v_sub_f32_e32 v139, v107, v138
	v_sub_f32_e32 v138, v106, v138
	v_pk_mul_f32 v[138:139], v[138:139], v[22:23]
	v_mov_b32_e32 v23, v22
	v_pk_mul_f32 v[22:23], v[146:147], v[22:23]
	v_mov_b32_e32 v19, 0
	v_pk_fma_f32 v[22:23], v[22:23], v[142:143], v[158:159]
	v_pk_fma_f32 v[138:139], v[138:139], v[140:141], v[156:157]
	s_nop 0
	v_cvt_pk_bf16_f32 v138, v138, v139
	v_cvt_pk_bf16_f32 v139, v22, v23
	v_lshl_add_u64 v[22:23], v[144:145], 0, v[18:19]
	global_store_dwordx2 v[22:23], v[138:139], off offset:32
.LBB0_1425:
	v_mov_b64_e32 v[156:157], v[224:225]
	v_mov_b64_e32 v[158:159], v[226:227]
	v_or_b32_e32 v22, 32, v128
	v_mov_b32_e32 v23, 0
	v_lshl_add_u64 v[146:147], s[42:43], 0, v[22:23]
	v_lshl_add_u32 v22, v22, 6, 0
	ds_read_b128 v[138:141], v22
	ds_read_b128 v[160:163], v22 offset:16
	ds_read2_b64 v[164:167], v22 offset0:4 offset1:6
	v_mov_b32_e32 v17, 0x358637bd
	s_mov_b32 s12, 0x3c800000
	s_waitcnt lgkmcnt(2)
	v_mov_b32_e32 v142, v138
	s_waitcnt lgkmcnt(1)
	v_pk_add_f32 v[138:139], v[138:139], v[160:161]
	s_waitcnt lgkmcnt(0)
	v_mov_b32_e32 v143, v164
	v_mov_b32_e32 v164, v160
	v_mov_b32_e32 v165, v166
	v_add_f32_e32 v140, v140, v162
	v_pk_add_f32 v[142:143], v[142:143], v[164:165]
	v_pk_mov_b32 v[138:139], v[138:139], v[140:141] op_sel:[1,0]
	v_add_f32_e32 v129, v142, v143
	s_mov_b32 s14, 0x800000
	v_pk_mul_f32 v[138:139], v[138:139], s[12:13] op_sel_hi:[1,0]
	v_fmac_f32_e32 v17, 0x3c000000, v129
	v_fma_f32 v129, -v138, v138, v139
	v_mul_f32_e32 v139, 0x4b800000, v17
	v_cmp_gt_f32_e64 s[12:13], s14, v17
	v_max_f32_e32 v129, 0, v129
	v_add_f32_e32 v129, 0x358637bd, v129
	v_cndmask_b32_e64 v17, v17, v139, s[12:13]
	v_rsq_f32_e32 v17, v17
	v_mul_f32_e32 v139, 0x4b800000, v129
	v_cmp_gt_f32_e64 s[14:15], s14, v129
	v_mov_b32_e32 v19, v23
	v_lshlrev_b64 v[22:23], 8, v[146:147]
	v_cndmask_b32_e64 v129, v129, v139, s[14:15]
	v_lshl_add_u64 v[22:23], s[40:41], 0, v[22:23]
	v_rsq_f32_e32 v129, v129
	v_lshl_add_u64 v[140:141], v[22:23], 0, v[18:19]
	v_mul_f32_e32 v19, 0x45800000, v17
	v_cndmask_b32_e64 v142, v17, v19, s[12:13]
	v_pk_mul_f32 v[160:161], v[100:101], v[142:143] op_sel_hi:[1,0]
	v_pk_mul_f32 v[162:163], v[102:103], v[142:143] op_sel_hi:[1,0]
	v_mul_f32_e32 v17, 0x45800000, v129
	s_and_b64 vcc, exec, s[10:11]
	v_lshlrev_b64 v[144:145], 7, v[146:147]
	v_cndmask_b32_e64 v22, v129, v17, s[14:15]
	s_mov_b64 s[12:13], -1
	v_pk_mul_f32 v[158:159], v[158:159], v[162:163]
	v_pk_mul_f32 v[156:157], v[156:157], v[160:161]
	s_nop 0
	v_cvt_pk_bf16_f32 v156, v156, v157
	v_cvt_pk_bf16_f32 v157, v158, v159
	global_store_dwordx2 v[140:141], v[156:157], off
	s_cbranch_vccnz .LBB0_1429
	s_and_b64 vcc, exec, s[6:7]
	s_cbranch_vccnz .LBB0_1428
	v_lshlrev_b64 v[146:147], 6, v[146:147]
	v_lshl_add_u64 v[146:147], s[38:39], 0, v[146:147]
	v_lshlrev_b32_e32 v156, 2, v155
	v_mov_b32_e32 v157, 0
	s_mov_b32 s12, 0x3d000000
	v_lshl_add_u64 v[146:147], v[146:147], 0, v[156:157]
	v_pk_mul_f32 v[158:159], v[92:93], s[12:13] op_sel_hi:[1,0]
	v_pk_mul_f32 v[156:157], v[94:95], s[12:13] op_sel_hi:[1,0]
	global_store_dwordx4 v[146:147], v[156:159], off sc1

.LBB0_1429:
	v_mov_b32_e32 v143, v142
	v_mov_b32_e32 v23, v22
	s_andn2_b64 vcc, exec, s[12:13]
	v_lshl_add_u64 v[144:145], s[36:37], 0, v[144:145]
	s_cbranch_vccnz .LBB0_1431
	v_mov_b64_e32 v[156:157], v[232:233]
	v_mov_b64_e32 v[158:159], v[234:235]
	v_mov_b64_e32 v[160:161], v[236:237]
	v_mov_b64_e32 v[162:163], v[238:239]
	v_sub_f32_e32 v147, v93, v138
	v_sub_f32_e32 v146, v92, v138
	v_sub_f32_e32 v165, v95, v138
	v_sub_f32_e32 v164, v94, v138
	v_mov_b32_e32 v166, v22
	v_mov_b32_e32 v167, v22
	v_pk_mul_f32 v[164:165], v[164:165], v[22:23]
	v_pk_mul_f32 v[146:147], v[146:147], v[166:167]
	v_mov_b32_e32 v19, 0
	v_pk_fma_f32 v[146:147], v[146:147], v[158:159], v[162:163]
	v_pk_fma_f32 v[156:157], v[164:165], v[156:157], v[160:161]
	s_nop 0
	v_cvt_pk_bf16_f32 v156, v156, v157
	v_cvt_pk_bf16_f32 v157, v146, v147
	v_lshl_add_u64 v[146:147], v[144:145], 0, v[18:19]
	global_store_dwordx2 v[146:147], v[156:157], off
.LBB0_1431:
	v_mov_b64_e32 v[156:157], v[228:229]
	v_mov_b64_e32 v[158:159], v[230:231]
	v_mov_b32_e32 v146, v142
	v_mov_b32_e32 v147, v142
	v_pk_mul_f32 v[142:143], v[96:97], v[142:143]
	v_pk_mul_f32 v[146:147], v[98:99], v[146:147]
	s_and_b64 vcc, exec, s[8:9]
	v_pk_mul_f32 v[146:147], v[146:147], v[158:159]
	v_pk_mul_f32 v[142:143], v[142:143], v[156:157]
	s_nop 0
	v_cvt_pk_bf16_f32 v142, v142, v143
	v_cvt_pk_bf16_f32 v143, v146, v147
	global_store_dwordx2 v[140:141], v[142:143], off offset:32
	s_cbranch_vccnz .LBB0_1433
	v_mov_b64_e32 v[140:141], v[240:241]
	v_mov_b64_e32 v[142:143], v[242:243]
	v_mov_b64_e32 v[156:157], v[244:245]
	v_mov_b64_e32 v[158:159], v[246:247]
	v_sub_f32_e32 v147, v89, v138
	v_sub_f32_e32 v146, v88, v138
	v_sub_f32_e32 v139, v91, v138
	v_sub_f32_e32 v138, v90, v138
	v_pk_mul_f32 v[138:139], v[138:139], v[22:23]
	v_mov_b32_e32 v23, v22
	v_pk_mul_f32 v[22:23], v[146:147], v[22:23]
	v_mov_b32_e32 v19, 0
	v_pk_fma_f32 v[22:23], v[22:23], v[142:143], v[158:159]
	v_pk_fma_f32 v[138:139], v[138:139], v[140:141], v[156:157]
	s_nop 0
	v_cvt_pk_bf16_f32 v138, v138, v139
	v_cvt_pk_bf16_f32 v139, v22, v23
	v_lshl_add_u64 v[22:23], v[144:145], 0, v[18:19]
	global_store_dwordx2 v[22:23], v[138:139], off offset:32
.LBB0_1433:
	v_mov_b64_e32 v[156:157], v[224:225]
	v_mov_b64_e32 v[158:159], v[226:227]
	v_or_b32_e32 v22, 48, v128
	v_mov_b32_e32 v23, 0
	v_lshl_add_u64 v[146:147], s[42:43], 0, v[22:23]
	v_lshl_add_u32 v22, v22, 6, 0
	ds_read_b128 v[138:141], v22
	ds_read_b128 v[160:163], v22 offset:16
	ds_read2_b64 v[164:167], v22 offset0:4 offset1:6
	v_mov_b32_e32 v17, 0x358637bd
	s_mov_b32 s12, 0x3c800000
	s_waitcnt lgkmcnt(2)
	v_mov_b32_e32 v142, v138
	s_waitcnt lgkmcnt(1)
	v_pk_add_f32 v[138:139], v[138:139], v[160:161]
	s_waitcnt lgkmcnt(0)
	v_mov_b32_e32 v143, v164
	v_mov_b32_e32 v164, v160
	v_mov_b32_e32 v165, v166
	v_add_f32_e32 v140, v140, v162
	v_pk_add_f32 v[142:143], v[142:143], v[164:165]
	v_pk_mov_b32 v[138:139], v[138:139], v[140:141] op_sel:[1,0]
	v_add_f32_e32 v129, v142, v143
	s_mov_b32 s14, 0x800000
	v_pk_mul_f32 v[138:139], v[138:139], s[12:13] op_sel_hi:[1,0]
	v_fmac_f32_e32 v17, 0x3c000000, v129
	v_fma_f32 v129, -v138, v138, v139
	v_mul_f32_e32 v139, 0x4b800000, v17
	v_cmp_gt_f32_e64 s[12:13], s14, v17
	v_max_f32_e32 v129, 0, v129
	v_add_f32_e32 v129, 0x358637bd, v129
	v_cndmask_b32_e64 v17, v17, v139, s[12:13]
	v_rsq_f32_e32 v17, v17
	v_mul_f32_e32 v139, 0x4b800000, v129
	v_cmp_gt_f32_e64 s[14:15], s14, v129
	v_mov_b32_e32 v19, v23
	v_lshlrev_b64 v[22:23], 8, v[146:147]
	v_cndmask_b32_e64 v129, v129, v139, s[14:15]
	v_lshl_add_u64 v[22:23], s[40:41], 0, v[22:23]
	v_rsq_f32_e32 v129, v129
	v_lshl_add_u64 v[140:141], v[22:23], 0, v[18:19]
	v_mul_f32_e32 v19, 0x45800000, v17
	v_cndmask_b32_e64 v142, v17, v19, s[12:13]
	v_pk_mul_f32 v[160:161], v[84:85], v[142:143] op_sel_hi:[1,0]
	v_pk_mul_f32 v[162:163], v[86:87], v[142:143] op_sel_hi:[1,0]
	v_mul_f32_e32 v17, 0x45800000, v129
	s_and_b64 vcc, exec, s[10:11]
	v_lshlrev_b64 v[144:145], 7, v[146:147]
	v_cndmask_b32_e64 v22, v129, v17, s[14:15]
	s_mov_b64 s[12:13], -1
	v_pk_mul_f32 v[158:159], v[158:159], v[162:163]
	v_pk_mul_f32 v[156:157], v[156:157], v[160:161]
	s_nop 0
	v_cvt_pk_bf16_f32 v156, v156, v157
	v_cvt_pk_bf16_f32 v157, v158, v159
	global_store_dwordx2 v[140:141], v[156:157], off
	s_cbranch_vccnz .LBB0_1437
	s_and_b64 vcc, exec, s[6:7]
	s_cbranch_vccnz .LBB0_1436
	v_lshlrev_b64 v[146:147], 6, v[146:147]
	v_lshl_add_u64 v[146:147], s[38:39], 0, v[146:147]
	v_lshlrev_b32_e32 v156, 2, v155
	v_mov_b32_e32 v157, 0
	s_mov_b32 s12, 0x3d000000
	v_lshl_add_u64 v[146:147], v[146:147], 0, v[156:157]
	v_pk_mul_f32 v[158:159], v[76:77], s[12:13] op_sel_hi:[1,0]
	v_pk_mul_f32 v[156:157], v[78:79], s[12:13] op_sel_hi:[1,0]
	global_store_dwordx4 v[146:147], v[156:159], off sc1

.LBB0_1437:
	v_mov_b32_e32 v143, v142
	v_mov_b32_e32 v23, v22
	s_andn2_b64 vcc, exec, s[12:13]
	v_lshl_add_u64 v[144:145], s[36:37], 0, v[144:145]
	s_cbranch_vccnz .LBB0_1439
	v_mov_b64_e32 v[156:157], v[232:233]
	v_mov_b64_e32 v[158:159], v[234:235]
	v_mov_b64_e32 v[160:161], v[236:237]
	v_mov_b64_e32 v[162:163], v[238:239]
	v_sub_f32_e32 v147, v77, v138
	v_sub_f32_e32 v146, v76, v138
	v_sub_f32_e32 v165, v79, v138
	v_sub_f32_e32 v164, v78, v138
	v_mov_b32_e32 v166, v22
	v_mov_b32_e32 v167, v22
	v_pk_mul_f32 v[164:165], v[164:165], v[22:23]
	v_pk_mul_f32 v[146:147], v[146:147], v[166:167]
	v_mov_b32_e32 v19, 0
	v_pk_fma_f32 v[146:147], v[146:147], v[158:159], v[162:163]
	v_pk_fma_f32 v[156:157], v[164:165], v[156:157], v[160:161]
	s_nop 0
	v_cvt_pk_bf16_f32 v156, v156, v157
	v_cvt_pk_bf16_f32 v157, v146, v147
	v_lshl_add_u64 v[146:147], v[144:145], 0, v[18:19]
	global_store_dwordx2 v[146:147], v[156:157], off
.LBB0_1439:
	v_mov_b64_e32 v[156:157], v[228:229]
	v_mov_b64_e32 v[158:159], v[230:231]
	v_mov_b32_e32 v146, v142
	v_mov_b32_e32 v147, v142
	v_pk_mul_f32 v[142:143], v[80:81], v[142:143]
	v_pk_mul_f32 v[146:147], v[82:83], v[146:147]
	s_and_b64 vcc, exec, s[8:9]
	v_pk_mul_f32 v[146:147], v[146:147], v[158:159]
	v_pk_mul_f32 v[142:143], v[142:143], v[156:157]
	s_nop 0
	v_cvt_pk_bf16_f32 v142, v142, v143
	v_cvt_pk_bf16_f32 v143, v146, v147
	global_store_dwordx2 v[140:141], v[142:143], off offset:32
	s_cbranch_vccnz .LBB0_1441
	v_mov_b64_e32 v[140:141], v[240:241]
	v_mov_b64_e32 v[142:143], v[242:243]
	v_mov_b64_e32 v[156:157], v[244:245]
	v_mov_b64_e32 v[158:159], v[246:247]
	v_sub_f32_e32 v147, v73, v138
	v_sub_f32_e32 v146, v72, v138
	v_sub_f32_e32 v139, v75, v138
	v_sub_f32_e32 v138, v74, v138
	v_pk_mul_f32 v[138:139], v[138:139], v[22:23]
	v_mov_b32_e32 v23, v22
	v_pk_mul_f32 v[22:23], v[146:147], v[22:23]
	v_mov_b32_e32 v19, 0
	v_pk_fma_f32 v[22:23], v[22:23], v[142:143], v[158:159]
	v_pk_fma_f32 v[138:139], v[138:139], v[140:141], v[156:157]
	s_nop 0
	v_cvt_pk_bf16_f32 v138, v138, v139
	v_cvt_pk_bf16_f32 v139, v22, v23
	v_lshl_add_u64 v[22:23], v[144:145], 0, v[18:19]
	global_store_dwordx2 v[22:23], v[138:139], off offset:32
.LBB0_1441:
	v_mov_b64_e32 v[156:157], v[224:225]
	v_mov_b64_e32 v[158:159], v[226:227]
	v_add_u32_e32 v22, 0x80, v128
	v_mov_b32_e32 v23, 0
	v_lshl_add_u64 v[146:147], s[42:43], 0, v[22:23]
	v_lshl_add_u32 v22, v22, 6, 0
	ds_read_b128 v[138:141], v22
	ds_read_b128 v[160:163], v22 offset:16
	ds_read2_b64 v[164:167], v22 offset0:4 offset1:6
	v_mov_b32_e32 v17, 0x358637bd
	s_mov_b32 s12, 0x3c800000
	s_waitcnt lgkmcnt(2)
	v_mov_b32_e32 v142, v138
	s_waitcnt lgkmcnt(1)
	v_pk_add_f32 v[138:139], v[138:139], v[160:161]
	s_waitcnt lgkmcnt(0)
	v_mov_b32_e32 v143, v164
	v_mov_b32_e32 v164, v160
	v_mov_b32_e32 v165, v166
	v_add_f32_e32 v140, v140, v162
	v_pk_add_f32 v[142:143], v[142:143], v[164:165]
	v_pk_mov_b32 v[138:139], v[138:139], v[140:141] op_sel:[1,0]
	v_add_f32_e32 v129, v142, v143
	s_mov_b32 s14, 0x800000
	v_pk_mul_f32 v[138:139], v[138:139], s[12:13] op_sel_hi:[1,0]
	v_fmac_f32_e32 v17, 0x3c000000, v129
	v_fma_f32 v129, -v138, v138, v139
	v_mul_f32_e32 v139, 0x4b800000, v17
	v_cmp_gt_f32_e64 s[12:13], s14, v17
	v_max_f32_e32 v129, 0, v129
	v_add_f32_e32 v129, 0x358637bd, v129
	v_cndmask_b32_e64 v17, v17, v139, s[12:13]
	v_rsq_f32_e32 v17, v17
	v_mul_f32_e32 v139, 0x4b800000, v129
	v_cmp_gt_f32_e64 s[14:15], s14, v129
	v_mov_b32_e32 v19, v23
	v_lshlrev_b64 v[22:23], 8, v[146:147]
	v_cndmask_b32_e64 v129, v129, v139, s[14:15]
	v_lshl_add_u64 v[22:23], s[40:41], 0, v[22:23]
	v_rsq_f32_e32 v129, v129
	v_lshl_add_u64 v[140:141], v[22:23], 0, v[18:19]
	v_mul_f32_e32 v19, 0x45800000, v17
	v_cndmask_b32_e64 v142, v17, v19, s[12:13]
	v_pk_mul_f32 v[160:161], v[70:71], v[142:143] op_sel_hi:[1,0]
	v_pk_mul_f32 v[162:163], v[68:69], v[142:143] op_sel_hi:[1,0]
	v_mul_f32_e32 v17, 0x45800000, v129
	s_and_b64 vcc, exec, s[10:11]
	v_lshlrev_b64 v[144:145], 7, v[146:147]
	v_cndmask_b32_e64 v22, v129, v17, s[14:15]
	s_mov_b64 s[12:13], -1
	v_pk_mul_f32 v[158:159], v[158:159], v[162:163]
	v_pk_mul_f32 v[156:157], v[156:157], v[160:161]
	s_nop 0
	v_cvt_pk_bf16_f32 v156, v156, v157
	v_cvt_pk_bf16_f32 v157, v158, v159
	global_store_dwordx2 v[140:141], v[156:157], off
	s_cbranch_vccnz .LBB0_1445
	s_and_b64 vcc, exec, s[6:7]
	s_cbranch_vccnz .LBB0_1444
	v_lshlrev_b64 v[146:147], 6, v[146:147]
	v_lshl_add_u64 v[146:147], s[38:39], 0, v[146:147]
	v_lshlrev_b32_e32 v156, 2, v155
	v_mov_b32_e32 v157, 0
	s_mov_b32 s12, 0x3d000000
	v_lshl_add_u64 v[146:147], v[146:147], 0, v[156:157]
	v_pk_mul_f32 v[158:159], v[60:61], s[12:13] op_sel_hi:[1,0]
	v_pk_mul_f32 v[156:157], v[62:63], s[12:13] op_sel_hi:[1,0]
	global_store_dwordx4 v[146:147], v[156:159], off sc1

.LBB0_1445:
	v_mov_b32_e32 v143, v142
	v_mov_b32_e32 v23, v22
	s_andn2_b64 vcc, exec, s[12:13]
	v_lshl_add_u64 v[144:145], s[36:37], 0, v[144:145]
	s_cbranch_vccnz .LBB0_1447
	v_mov_b64_e32 v[156:157], v[232:233]
	v_mov_b64_e32 v[158:159], v[234:235]
	v_mov_b64_e32 v[160:161], v[236:237]
	v_mov_b64_e32 v[162:163], v[238:239]
	v_sub_f32_e32 v147, v61, v138
	v_sub_f32_e32 v146, v60, v138
	v_sub_f32_e32 v165, v63, v138
	v_sub_f32_e32 v164, v62, v138
	v_mov_b32_e32 v166, v22
	v_mov_b32_e32 v167, v22
	v_pk_mul_f32 v[164:165], v[164:165], v[22:23]
	v_pk_mul_f32 v[146:147], v[146:147], v[166:167]
	v_mov_b32_e32 v19, 0
	v_pk_fma_f32 v[146:147], v[146:147], v[158:159], v[162:163]
	v_pk_fma_f32 v[156:157], v[164:165], v[156:157], v[160:161]
	s_nop 0
	v_cvt_pk_bf16_f32 v156, v156, v157
	v_cvt_pk_bf16_f32 v157, v146, v147
	v_lshl_add_u64 v[146:147], v[144:145], 0, v[18:19]
	global_store_dwordx2 v[146:147], v[156:157], off
.LBB0_1447:
	v_mov_b64_e32 v[156:157], v[228:229]
	v_mov_b64_e32 v[158:159], v[230:231]
	v_mov_b32_e32 v146, v142
	v_mov_b32_e32 v147, v142
	v_pk_mul_f32 v[142:143], v[66:67], v[142:143]
	v_pk_mul_f32 v[146:147], v[64:65], v[146:147]
	s_and_b64 vcc, exec, s[8:9]
	v_pk_mul_f32 v[146:147], v[146:147], v[158:159]
	v_pk_mul_f32 v[142:143], v[142:143], v[156:157]
	s_nop 0
	v_cvt_pk_bf16_f32 v142, v142, v143
	v_cvt_pk_bf16_f32 v143, v146, v147
	global_store_dwordx2 v[140:141], v[142:143], off offset:32
	s_cbranch_vccnz .LBB0_1449
	v_mov_b64_e32 v[140:141], v[240:241]
	v_mov_b64_e32 v[142:143], v[242:243]
	v_mov_b64_e32 v[156:157], v[244:245]
	v_mov_b64_e32 v[158:159], v[246:247]
	v_sub_f32_e32 v147, v57, v138
	v_sub_f32_e32 v146, v56, v138
	v_sub_f32_e32 v139, v59, v138
	v_sub_f32_e32 v138, v58, v138
	v_pk_mul_f32 v[138:139], v[138:139], v[22:23]
	v_mov_b32_e32 v23, v22
	v_pk_mul_f32 v[22:23], v[146:147], v[22:23]
	v_mov_b32_e32 v19, 0
	v_pk_fma_f32 v[22:23], v[22:23], v[142:143], v[158:159]
	v_pk_fma_f32 v[138:139], v[138:139], v[140:141], v[156:157]
	s_nop 0
	v_cvt_pk_bf16_f32 v138, v138, v139
	v_cvt_pk_bf16_f32 v139, v22, v23
	v_lshl_add_u64 v[22:23], v[144:145], 0, v[18:19]
	global_store_dwordx2 v[22:23], v[138:139], off offset:32
.LBB0_1449:
	v_mov_b64_e32 v[156:157], v[224:225]
	v_mov_b64_e32 v[158:159], v[226:227]
	v_add_u32_e32 v22, 0x90, v128
	v_mov_b32_e32 v23, 0
	v_lshl_add_u64 v[146:147], s[42:43], 0, v[22:23]
	v_lshl_add_u32 v22, v22, 6, 0
	ds_read_b128 v[138:141], v22
	ds_read_b128 v[160:163], v22 offset:16
	ds_read2_b64 v[164:167], v22 offset0:4 offset1:6
	v_mov_b32_e32 v17, 0x358637bd
	s_mov_b32 s12, 0x3c800000
	s_waitcnt lgkmcnt(2)
	v_mov_b32_e32 v142, v138
	s_waitcnt lgkmcnt(1)
	v_pk_add_f32 v[138:139], v[138:139], v[160:161]
	s_waitcnt lgkmcnt(0)
	v_mov_b32_e32 v143, v164
	v_mov_b32_e32 v164, v160
	v_mov_b32_e32 v165, v166
	v_add_f32_e32 v140, v140, v162
	v_pk_add_f32 v[142:143], v[142:143], v[164:165]
	v_pk_mov_b32 v[138:139], v[138:139], v[140:141] op_sel:[1,0]
	v_add_f32_e32 v129, v142, v143
	s_mov_b32 s14, 0x800000
	v_pk_mul_f32 v[138:139], v[138:139], s[12:13] op_sel_hi:[1,0]
	v_fmac_f32_e32 v17, 0x3c000000, v129
	v_fma_f32 v129, -v138, v138, v139
	v_mul_f32_e32 v139, 0x4b800000, v17
	v_cmp_gt_f32_e64 s[12:13], s14, v17
	v_max_f32_e32 v129, 0, v129
	v_add_f32_e32 v129, 0x358637bd, v129
	v_cndmask_b32_e64 v17, v17, v139, s[12:13]
	v_rsq_f32_e32 v17, v17
	v_mul_f32_e32 v139, 0x4b800000, v129
	v_cmp_gt_f32_e64 s[14:15], s14, v129
	v_mov_b32_e32 v19, v23
	v_lshlrev_b64 v[22:23], 8, v[146:147]
	v_cndmask_b32_e64 v129, v129, v139, s[14:15]
	v_lshl_add_u64 v[22:23], s[40:41], 0, v[22:23]
	v_rsq_f32_e32 v129, v129
	v_lshl_add_u64 v[140:141], v[22:23], 0, v[18:19]
	v_mul_f32_e32 v19, 0x45800000, v17
	v_cndmask_b32_e64 v142, v17, v19, s[12:13]
	v_pk_mul_f32 v[160:161], v[52:53], v[142:143] op_sel_hi:[1,0]
	v_pk_mul_f32 v[162:163], v[54:55], v[142:143] op_sel_hi:[1,0]
	v_mul_f32_e32 v17, 0x45800000, v129
	s_and_b64 vcc, exec, s[10:11]
	v_lshlrev_b64 v[144:145], 7, v[146:147]
	v_cndmask_b32_e64 v22, v129, v17, s[14:15]
	s_mov_b64 s[12:13], -1
	v_pk_mul_f32 v[158:159], v[158:159], v[162:163]
	v_pk_mul_f32 v[156:157], v[156:157], v[160:161]
	s_nop 0
	v_cvt_pk_bf16_f32 v156, v156, v157
	v_cvt_pk_bf16_f32 v157, v158, v159
	global_store_dwordx2 v[140:141], v[156:157], off
	s_cbranch_vccnz .LBB0_1453
	s_and_b64 vcc, exec, s[6:7]
	s_cbranch_vccnz .LBB0_1452
	v_lshlrev_b64 v[146:147], 6, v[146:147]
	v_lshl_add_u64 v[146:147], s[38:39], 0, v[146:147]
	v_lshlrev_b32_e32 v156, 2, v155
	v_mov_b32_e32 v157, 0
	s_mov_b32 s12, 0x3d000000
	v_lshl_add_u64 v[146:147], v[146:147], 0, v[156:157]
	v_pk_mul_f32 v[158:159], v[44:45], s[12:13] op_sel_hi:[1,0]
	v_pk_mul_f32 v[156:157], v[46:47], s[12:13] op_sel_hi:[1,0]
	global_store_dwordx4 v[146:147], v[156:159], off sc1

.LBB0_1453:
	v_mov_b32_e32 v143, v142
	v_mov_b32_e32 v23, v22
	s_andn2_b64 vcc, exec, s[12:13]
	v_lshl_add_u64 v[144:145], s[36:37], 0, v[144:145]
	s_cbranch_vccnz .LBB0_1455
	v_mov_b64_e32 v[156:157], v[232:233]
	v_mov_b64_e32 v[158:159], v[234:235]
	v_mov_b64_e32 v[160:161], v[236:237]
	v_mov_b64_e32 v[162:163], v[238:239]
	v_sub_f32_e32 v147, v45, v138
	v_sub_f32_e32 v146, v44, v138
	v_sub_f32_e32 v165, v47, v138
	v_sub_f32_e32 v164, v46, v138
	v_mov_b32_e32 v166, v22
	v_mov_b32_e32 v167, v22
	v_pk_mul_f32 v[164:165], v[164:165], v[22:23]
	v_pk_mul_f32 v[146:147], v[146:147], v[166:167]
	v_mov_b32_e32 v19, 0
	v_pk_fma_f32 v[146:147], v[146:147], v[158:159], v[162:163]
	v_pk_fma_f32 v[156:157], v[164:165], v[156:157], v[160:161]
	s_nop 0
	v_cvt_pk_bf16_f32 v156, v156, v157
	v_cvt_pk_bf16_f32 v157, v146, v147
	v_lshl_add_u64 v[146:147], v[144:145], 0, v[18:19]
	global_store_dwordx2 v[146:147], v[156:157], off
.LBB0_1455:
	v_mov_b64_e32 v[156:157], v[228:229]
	v_mov_b64_e32 v[158:159], v[230:231]
	v_mov_b32_e32 v146, v142
	v_mov_b32_e32 v147, v142
	v_pk_mul_f32 v[142:143], v[48:49], v[142:143]
	v_pk_mul_f32 v[146:147], v[50:51], v[146:147]
	s_and_b64 vcc, exec, s[8:9]
	v_pk_mul_f32 v[146:147], v[146:147], v[158:159]
	v_pk_mul_f32 v[142:143], v[142:143], v[156:157]
	s_nop 0
	v_cvt_pk_bf16_f32 v142, v142, v143
	v_cvt_pk_bf16_f32 v143, v146, v147
	global_store_dwordx2 v[140:141], v[142:143], off offset:32
	s_cbranch_vccnz .LBB0_1457
	v_mov_b64_e32 v[140:141], v[240:241]
	v_mov_b64_e32 v[142:143], v[242:243]
	v_mov_b64_e32 v[156:157], v[244:245]
	v_mov_b64_e32 v[158:159], v[246:247]
	v_sub_f32_e32 v147, v41, v138
	v_sub_f32_e32 v146, v40, v138
	v_sub_f32_e32 v139, v43, v138
	v_sub_f32_e32 v138, v42, v138
	v_pk_mul_f32 v[138:139], v[138:139], v[22:23]
	v_mov_b32_e32 v23, v22
	v_pk_mul_f32 v[22:23], v[146:147], v[22:23]
	v_mov_b32_e32 v19, 0
	v_pk_fma_f32 v[22:23], v[22:23], v[142:143], v[158:159]
	v_pk_fma_f32 v[138:139], v[138:139], v[140:141], v[156:157]
	s_nop 0
	v_cvt_pk_bf16_f32 v138, v138, v139
	v_cvt_pk_bf16_f32 v139, v22, v23
	v_lshl_add_u64 v[22:23], v[144:145], 0, v[18:19]
	global_store_dwordx2 v[22:23], v[138:139], off offset:32
.LBB0_1457:
	v_mov_b64_e32 v[156:157], v[224:225]
	v_mov_b64_e32 v[158:159], v[226:227]
	v_add_u32_e32 v22, 0xa0, v128
	v_mov_b32_e32 v23, 0
	v_lshl_add_u64 v[146:147], s[42:43], 0, v[22:23]
	v_lshl_add_u32 v22, v22, 6, 0
	ds_read_b128 v[138:141], v22
	ds_read_b128 v[160:163], v22 offset:16
	ds_read2_b64 v[164:167], v22 offset0:4 offset1:6
	v_mov_b32_e32 v17, 0x358637bd
	s_mov_b32 s12, 0x3c800000
	s_waitcnt lgkmcnt(2)
	v_mov_b32_e32 v142, v138
	s_waitcnt lgkmcnt(1)
	v_pk_add_f32 v[138:139], v[138:139], v[160:161]
	s_waitcnt lgkmcnt(0)
	v_mov_b32_e32 v143, v164
	v_mov_b32_e32 v164, v160
	v_mov_b32_e32 v165, v166
	v_add_f32_e32 v140, v140, v162
	v_pk_add_f32 v[142:143], v[142:143], v[164:165]
	v_pk_mov_b32 v[138:139], v[138:139], v[140:141] op_sel:[1,0]
	v_add_f32_e32 v129, v142, v143
	s_mov_b32 s14, 0x800000
	v_pk_mul_f32 v[138:139], v[138:139], s[12:13] op_sel_hi:[1,0]
	v_fmac_f32_e32 v17, 0x3c000000, v129
	v_fma_f32 v129, -v138, v138, v139
	v_mul_f32_e32 v139, 0x4b800000, v17
	v_cmp_gt_f32_e64 s[12:13], s14, v17
	v_max_f32_e32 v129, 0, v129
	v_add_f32_e32 v129, 0x358637bd, v129
	v_cndmask_b32_e64 v17, v17, v139, s[12:13]
	v_rsq_f32_e32 v17, v17
	v_mul_f32_e32 v139, 0x4b800000, v129
	v_cmp_gt_f32_e64 s[14:15], s14, v129
	v_mov_b32_e32 v19, v23
	v_lshlrev_b64 v[22:23], 8, v[146:147]
	v_cndmask_b32_e64 v129, v129, v139, s[14:15]
	v_lshl_add_u64 v[22:23], s[40:41], 0, v[22:23]
	v_rsq_f32_e32 v129, v129
	v_lshl_add_u64 v[140:141], v[22:23], 0, v[18:19]
	v_mul_f32_e32 v19, 0x45800000, v17
	v_cndmask_b32_e64 v142, v17, v19, s[12:13]
	v_pk_mul_f32 v[160:161], v[36:37], v[142:143] op_sel_hi:[1,0]
	v_pk_mul_f32 v[162:163], v[38:39], v[142:143] op_sel_hi:[1,0]
	v_mul_f32_e32 v17, 0x45800000, v129
	s_and_b64 vcc, exec, s[10:11]
	v_lshlrev_b64 v[144:145], 7, v[146:147]
	v_cndmask_b32_e64 v22, v129, v17, s[14:15]
	s_mov_b64 s[12:13], -1
	v_pk_mul_f32 v[158:159], v[158:159], v[162:163]
	v_pk_mul_f32 v[156:157], v[156:157], v[160:161]
	s_nop 0
	v_cvt_pk_bf16_f32 v156, v156, v157
	v_cvt_pk_bf16_f32 v157, v158, v159
	global_store_dwordx2 v[140:141], v[156:157], off
	s_cbranch_vccnz .LBB0_1461
	s_and_b64 vcc, exec, s[6:7]
	s_cbranch_vccnz .LBB0_1460
	v_lshlrev_b64 v[146:147], 6, v[146:147]
	v_lshl_add_u64 v[146:147], s[38:39], 0, v[146:147]
	v_lshlrev_b32_e32 v156, 2, v155
	v_mov_b32_e32 v157, 0
	s_mov_b32 s12, 0x3d000000
	v_lshl_add_u64 v[146:147], v[146:147], 0, v[156:157]
	v_pk_mul_f32 v[158:159], v[28:29], s[12:13] op_sel_hi:[1,0]
	v_pk_mul_f32 v[156:157], v[30:31], s[12:13] op_sel_hi:[1,0]
	global_store_dwordx4 v[146:147], v[156:159], off sc1

.LBB0_1461:
	v_mov_b32_e32 v143, v142
	v_mov_b32_e32 v23, v22
	s_andn2_b64 vcc, exec, s[12:13]
	v_lshl_add_u64 v[144:145], s[36:37], 0, v[144:145]
	s_cbranch_vccnz .LBB0_1463
	v_mov_b64_e32 v[156:157], v[232:233]
	v_mov_b64_e32 v[158:159], v[234:235]
	v_mov_b64_e32 v[160:161], v[236:237]
	v_mov_b64_e32 v[162:163], v[238:239]
	v_sub_f32_e32 v147, v29, v138
	v_sub_f32_e32 v146, v28, v138
	v_sub_f32_e32 v165, v31, v138
	v_sub_f32_e32 v164, v30, v138
	v_mov_b32_e32 v166, v22
	v_mov_b32_e32 v167, v22
	v_pk_mul_f32 v[164:165], v[164:165], v[22:23]
	v_pk_mul_f32 v[146:147], v[146:147], v[166:167]
	v_mov_b32_e32 v19, 0
	v_pk_fma_f32 v[146:147], v[146:147], v[158:159], v[162:163]
	v_pk_fma_f32 v[156:157], v[164:165], v[156:157], v[160:161]
	s_nop 0
	v_cvt_pk_bf16_f32 v156, v156, v157
	v_cvt_pk_bf16_f32 v157, v146, v147
	v_lshl_add_u64 v[146:147], v[144:145], 0, v[18:19]
	global_store_dwordx2 v[146:147], v[156:157], off
.LBB0_1463:
	v_mov_b64_e32 v[156:157], v[228:229]
	v_mov_b64_e32 v[158:159], v[230:231]
	v_mov_b32_e32 v146, v142
	v_mov_b32_e32 v147, v142
	v_pk_mul_f32 v[142:143], v[32:33], v[142:143]
	v_pk_mul_f32 v[146:147], v[34:35], v[146:147]
	s_and_b64 vcc, exec, s[8:9]
	v_pk_mul_f32 v[146:147], v[146:147], v[158:159]
	v_pk_mul_f32 v[142:143], v[142:143], v[156:157]
	s_nop 0
	v_cvt_pk_bf16_f32 v142, v142, v143
	v_cvt_pk_bf16_f32 v143, v146, v147
	global_store_dwordx2 v[140:141], v[142:143], off offset:32
	s_cbranch_vccnz .LBB0_1465
	v_mov_b64_e32 v[140:141], v[240:241]
	v_mov_b64_e32 v[142:143], v[242:243]
	v_mov_b64_e32 v[156:157], v[244:245]
	v_mov_b64_e32 v[158:159], v[246:247]
	v_sub_f32_e32 v147, v25, v138
	v_sub_f32_e32 v146, v24, v138
	v_sub_f32_e32 v139, v27, v138
	v_sub_f32_e32 v138, v26, v138
	v_pk_mul_f32 v[138:139], v[138:139], v[22:23]
	v_mov_b32_e32 v23, v22
	v_pk_mul_f32 v[22:23], v[146:147], v[22:23]
	v_mov_b32_e32 v19, 0
	v_pk_fma_f32 v[22:23], v[22:23], v[142:143], v[158:159]
	v_pk_fma_f32 v[138:139], v[138:139], v[140:141], v[156:157]
	s_nop 0
	v_cvt_pk_bf16_f32 v138, v138, v139
	v_cvt_pk_bf16_f32 v139, v22, v23
	v_lshl_add_u64 v[22:23], v[144:145], 0, v[18:19]
	global_store_dwordx2 v[22:23], v[138:139], off offset:32
.LBB0_1465:
	v_mov_b64_e32 v[156:157], v[224:225]
	v_mov_b64_e32 v[158:159], v[226:227]
	v_add_u32_e32 v22, 0xb0, v128
	v_mov_b32_e32 v23, 0
	v_lshl_add_u64 v[146:147], s[42:43], 0, v[22:23]
	v_lshl_add_u32 v22, v22, 6, 0
	ds_read_b128 v[138:141], v22
	ds_read_b128 v[160:163], v22 offset:16
	ds_read2_b64 v[164:167], v22 offset0:4 offset1:6
	v_mov_b32_e32 v17, 0x358637bd
	s_mov_b32 s13, 0x800000
	s_waitcnt lgkmcnt(2)
	v_mov_b32_e32 v142, v138
	s_waitcnt lgkmcnt(1)
	v_pk_add_f32 v[138:139], v[138:139], v[160:161]
	s_waitcnt lgkmcnt(0)
	v_mov_b32_e32 v143, v164
	v_mov_b32_e32 v164, v160
	v_mov_b32_e32 v165, v166
	v_add_f32_e32 v140, v140, v162
	v_pk_add_f32 v[142:143], v[142:143], v[164:165]
	s_mov_b32 s12, 0x3c800000
	v_pk_mov_b32 v[138:139], v[138:139], v[140:141] op_sel:[1,0]
	v_add_f32_e32 v129, v142, v143
	v_pk_mul_f32 v[138:139], v[138:139], s[12:13] op_sel_hi:[1,0]
	v_fmac_f32_e32 v17, 0x3c000000, v129
	s_and_b64 vcc, exec, s[10:11]
	v_fma_f32 v129, -v138, v138, v139
	v_mul_f32_e32 v139, 0x4b800000, v17
	v_cmp_gt_f32_e64 s[10:11], s13, v17
	v_max_f32_e32 v129, 0, v129
	v_add_f32_e32 v129, 0x358637bd, v129
	v_cndmask_b32_e64 v17, v17, v139, s[10:11]
	v_rsq_f32_e32 v17, v17
	v_mul_f32_e32 v139, 0x4b800000, v129
	v_cmp_gt_f32_e64 s[12:13], s13, v129
	v_mov_b32_e32 v19, v23
	v_lshlrev_b64 v[22:23], 8, v[146:147]
	v_cndmask_b32_e64 v129, v129, v139, s[12:13]
	v_lshl_add_u64 v[22:23], s[40:41], 0, v[22:23]
	v_rsq_f32_e32 v129, v129
	v_lshl_add_u64 v[140:141], v[22:23], 0, v[18:19]
	v_mul_f32_e32 v19, 0x45800000, v17
	v_cndmask_b32_e64 v142, v17, v19, s[10:11]
	v_pk_mul_f32 v[160:161], v[14:15], v[142:143] op_sel_hi:[1,0]
	v_pk_mul_f32 v[162:163], v[10:11], v[142:143] op_sel_hi:[1,0]
	v_mul_f32_e32 v17, 0x45800000, v129
	v_lshlrev_b64 v[144:145], 7, v[146:147]
	v_cndmask_b32_e64 v22, v129, v17, s[12:13]
	s_mov_b64 s[10:11], -1
	v_pk_mul_f32 v[158:159], v[158:159], v[162:163]
	v_pk_mul_f32 v[156:157], v[156:157], v[160:161]
	s_nop 0
	v_cvt_pk_bf16_f32 v156, v156, v157
	v_cvt_pk_bf16_f32 v157, v158, v159
	global_store_dwordx2 v[140:141], v[156:157], off
	s_cbranch_vccnz .LBB0_1469
	s_and_b64 vcc, exec, s[6:7]
	s_cbranch_vccnz .LBB0_1468
	v_lshlrev_b64 v[146:147], 6, v[146:147]
	v_lshl_add_u64 v[146:147], s[38:39], 0, v[146:147]
	v_lshlrev_b32_e32 v156, 2, v155
	v_mov_b32_e32 v157, 0
	s_mov_b32 s6, 0x3d000000
	v_lshl_add_u64 v[146:147], v[146:147], 0, v[156:157]
	v_pk_mul_f32 v[158:159], v[6:7], s[6:7] op_sel_hi:[1,0]
	v_pk_mul_f32 v[156:157], v[4:5], s[6:7] op_sel_hi:[1,0]
	global_store_dwordx4 v[146:147], v[156:159], off sc1

.LBB0_1469:
	v_mov_b32_e32 v143, v142
	v_mov_b32_e32 v23, v22
	s_andn2_b64 vcc, exec, s[10:11]
	v_lshl_add_u64 v[144:145], s[36:37], 0, v[144:145]
	s_cbranch_vccnz .LBB0_1471
	v_mov_b64_e32 v[156:157], v[232:233]
	v_mov_b64_e32 v[158:159], v[234:235]
	v_mov_b64_e32 v[160:161], v[236:237]
	v_mov_b64_e32 v[162:163], v[238:239]
	v_sub_f32_e32 v147, v7, v138
	v_sub_f32_e32 v146, v6, v138
	v_sub_f32_e32 v165, v5, v138
	v_sub_f32_e32 v164, v4, v138
	v_mov_b32_e32 v166, v22
	v_mov_b32_e32 v167, v22
	v_pk_mul_f32 v[164:165], v[164:165], v[22:23]
	v_pk_mul_f32 v[146:147], v[146:147], v[166:167]
	v_mov_b32_e32 v19, 0
	v_pk_fma_f32 v[146:147], v[146:147], v[158:159], v[162:163]
	v_pk_fma_f32 v[156:157], v[164:165], v[156:157], v[160:161]
	s_nop 0
	v_cvt_pk_bf16_f32 v156, v156, v157
	v_cvt_pk_bf16_f32 v157, v146, v147
	v_lshl_add_u64 v[146:147], v[144:145], 0, v[18:19]
	global_store_dwordx2 v[146:147], v[156:157], off
.LBB0_1471:
	v_mov_b64_e32 v[156:157], v[228:229]
	v_mov_b64_e32 v[158:159], v[230:231]
	v_mov_b32_e32 v20, v142
	v_mov_b32_e32 v21, v142
	v_pk_mul_f32 v[142:143], v[12:13], v[142:143]
	v_pk_mul_f32 v[20:21], v[8:9], v[20:21]
	s_and_b64 vcc, exec, s[8:9]
	v_pk_mul_f32 v[20:21], v[20:21], v[158:159]
	v_pk_mul_f32 v[142:143], v[142:143], v[156:157]
	s_nop 0
	v_cvt_pk_bf16_f32 v142, v142, v143
	v_cvt_pk_bf16_f32 v143, v20, v21
	global_store_dwordx2 v[140:141], v[142:143], off offset:32
	s_cbranch_vccnz .LBB0_1473
	v_mov_b64_e32 v[140:141], v[240:241]
	v_mov_b64_e32 v[142:143], v[242:243]
	v_mov_b64_e32 v[156:157], v[244:245]
	v_mov_b64_e32 v[158:159], v[246:247]
	v_sub_f32_e32 v21, v1, v138
	v_sub_f32_e32 v20, v0, v138
	v_sub_f32_e32 v17, v3, v138
	v_sub_f32_e32 v16, v2, v138
	v_pk_mul_f32 v[20:21], v[20:21], v[22:23]
	v_mov_b32_e32 v23, v22
	v_pk_mul_f32 v[16:17], v[16:17], v[22:23]
	v_mov_b32_e32 v19, 0
	v_pk_fma_f32 v[16:17], v[16:17], v[142:143], v[158:159]
	v_pk_fma_f32 v[20:21], v[20:21], v[140:141], v[156:157]
	s_nop 0
	v_cvt_pk_bf16_f32 v20, v20, v21
	v_cvt_pk_bf16_f32 v21, v16, v17
	v_lshl_add_u64 v[16:17], v[144:145], 0, v[18:19]
	global_store_dwordx2 v[16:17], v[20:21], off offset:32
